# prep transposed write-out: 64 ds_read_u16 into distinct VGPRs with counted waits instead of 32 serialized read-pair drains
# baseline (speedup 1.0000x reference)
; DI void phase_prep(const Params& p, int l, int bid, int nblk, char* smem) {
;     ...
;     if (transposed) {
;       __syncthreads();
;       u16* dst = (pass == 1) ? (UT + ((size_t)(tid * 16 + b)) * TPB + pos0) : (TX + ((size_t)(b * 768 + (pass - 2) * 256 + tid)) * TPB + pos0);
; #pragma unroll
;       for (int pc = 0; pc < 8; ++pc) {
;         u32 wv[4];
; #pragma unroll
;         for (int e = 0; e < 4; ++e)
;           wv[e] = (u32)tile[(pc * 8 + 2 * e) * 264 + tid] | ((u32)tile[(pc * 8 + 2 * e + 1) * 264 + tid] << 16);
;         uint4 o = {wv[0], wv[1], wv[2], wv[3]};
;         *(uint4*)&dst[pc * 8] = o;
;       }
;       __syncthreads();
;     }
.LBB0_806:
	s_add_u32 s0, s96, s0
	s_addc_u32 s1, s97, s1
	v_mov_b64_e32 v[2:3], s[0:1]
	v_mad_i64_i32 v[0:1], s[0:1], v0, s9, v[2:3]
	s_ashr_i32 s45, s44, 31
	v_lshl_add_u64 v[4:5], s[44:45], 1, v[0:1]
	ds_read_u16 v32, v178
	ds_read_u16 v64, v178 offset:528
	ds_read_u16 v33, v178 offset:1056
	ds_read_u16 v65, v178 offset:1584
	ds_read_u16 v34, v178 offset:2112
	ds_read_u16 v66, v178 offset:2640
	ds_read_u16 v35, v178 offset:3168
	ds_read_u16 v67, v178 offset:3696
	ds_read_u16 v36, v178 offset:4224
	ds_read_u16 v68, v178 offset:4752
	ds_read_u16 v37, v178 offset:5280
	ds_read_u16 v69, v178 offset:5808
	ds_read_u16 v38, v178 offset:6336
	ds_read_u16 v70, v178 offset:6864
	ds_read_u16 v39, v178 offset:7392
	ds_read_u16 v71, v178 offset:7920
	ds_read_u16 v40, v178 offset:8448
	ds_read_u16 v148, v178 offset:8976
	ds_read_u16 v41, v178 offset:9504
	ds_read_u16 v149, v178 offset:10032
	ds_read_u16 v42, v178 offset:10560
	ds_read_u16 v150, v178 offset:11088
	ds_read_u16 v43, v178 offset:11616
	ds_read_u16 v151, v178 offset:12144
	ds_read_u16 v44, v178 offset:12672
	ds_read_u16 v152, v178 offset:13200
	ds_read_u16 v45, v178 offset:13728
	ds_read_u16 v153, v178 offset:14256
	ds_read_u16 v46, v178 offset:14784
	ds_read_u16 v154, v178 offset:15312
	ds_read_u16 v47, v178 offset:15840
	ds_read_u16 v155, v178 offset:16368
	ds_read_u16 v48, v178 offset:16896
	ds_read_u16 v156, v178 offset:17424
	ds_read_u16 v49, v178 offset:17952
	ds_read_u16 v157, v178 offset:18480
	ds_read_u16 v50, v178 offset:19008
	ds_read_u16 v158, v178 offset:19536
	ds_read_u16 v51, v178 offset:20064
	ds_read_u16 v159, v178 offset:20592
	ds_read_u16 v52, v178 offset:21120
	ds_read_u16 v160, v178 offset:21648
	ds_read_u16 v53, v178 offset:22176
	ds_read_u16 v161, v178 offset:22704
	ds_read_u16 v54, v178 offset:23232
	ds_read_u16 v162, v178 offset:23760
	ds_read_u16 v55, v178 offset:24288
	ds_read_u16 v163, v178 offset:24816
	ds_read_u16 v56, v178 offset:25344
	ds_read_u16 v164, v178 offset:25872
	ds_read_u16 v57, v178 offset:26400
	ds_read_u16 v165, v178 offset:26928
	ds_read_u16 v58, v178 offset:27456
	ds_read_u16 v166, v178 offset:27984
	ds_read_u16 v59, v178 offset:28512
	ds_read_u16 v167, v178 offset:29040
	ds_read_u16 v60, v178 offset:29568
	ds_read_u16 v168, v178 offset:30096
	ds_read_u16 v61, v178 offset:30624
	ds_read_u16 v169, v178 offset:31152
	ds_read_u16 v62, v178 offset:31680
	ds_read_u16 v0, v178 offset:32208
	ds_read_u16 v63, v178 offset:32736
	ds_read_u16 v1, v178 offset:33264
	s_waitcnt lgkmcnt(15)
	v_lshl_or_b32 v32, v64, 16, v32
	v_lshl_or_b32 v33, v65, 16, v33
	v_lshl_or_b32 v34, v66, 16, v34
	v_lshl_or_b32 v35, v67, 16, v35
	global_store_dwordx4 v[4:5], v[32:35], off
	v_lshl_or_b32 v36, v68, 16, v36
	v_lshl_or_b32 v37, v69, 16, v37
	v_lshl_or_b32 v38, v70, 16, v38
	v_lshl_or_b32 v39, v71, 16, v39
	global_store_dwordx4 v[4:5], v[36:39], off offset:16
	v_lshl_or_b32 v40, v148, 16, v40
	v_lshl_or_b32 v41, v149, 16, v41
	v_lshl_or_b32 v42, v150, 16, v42
	v_lshl_or_b32 v43, v151, 16, v43
	global_store_dwordx4 v[4:5], v[40:43], off offset:32
	v_lshl_or_b32 v44, v152, 16, v44
	v_lshl_or_b32 v45, v153, 16, v45
	v_lshl_or_b32 v46, v154, 16, v46
	v_lshl_or_b32 v47, v155, 16, v47
	global_store_dwordx4 v[4:5], v[44:47], off offset:48
	v_lshl_or_b32 v48, v156, 16, v48
	v_lshl_or_b32 v49, v157, 16, v49
	v_lshl_or_b32 v50, v158, 16, v50
	v_lshl_or_b32 v51, v159, 16, v51
	global_store_dwordx4 v[4:5], v[48:51], off offset:64
	v_lshl_or_b32 v52, v160, 16, v52
	v_lshl_or_b32 v53, v161, 16, v53
	v_lshl_or_b32 v54, v162, 16, v54
	v_lshl_or_b32 v55, v163, 16, v55
	global_store_dwordx4 v[4:5], v[52:55], off offset:80
	s_waitcnt lgkmcnt(8)
	v_lshl_or_b32 v56, v164, 16, v56
	v_lshl_or_b32 v57, v165, 16, v57
	v_lshl_or_b32 v58, v166, 16, v58
	v_lshl_or_b32 v59, v167, 16, v59
	global_store_dwordx4 v[4:5], v[56:59], off offset:96
	s_waitcnt lgkmcnt(0)
	v_lshl_or_b32 v60, v168, 16, v60
	v_lshl_or_b32 v61, v169, 16, v61
	v_lshl_or_b32 v62, v0, 16, v62
	v_lshl_or_b32 v63, v1, 16, v63
	global_store_dwordx4 v[4:5], v[60:63], off offset:112
	s_barrier
